# v35
# speedup vs baseline: 1.0125x; 1.0040x over previous
; DI float fast_exp2(float x) { return __builtin_amdgcn_exp2f(x); }
; DI void mla_item(const Params& p, int b, int h, int qb) {
;     ...
;       float mx = sa[0][0];
;       #pragma unroll
;       for (int sub = 0; sub < NSUB; ++sub) for (int i = 0; i < 16; ++i) mx = fmaxf(mx, sa[sub][i]);
;       mx = fmaxf(mx, __shfl_xor(mx, 32));
;       const float mnew = fmaxf(mrun, mx);
;       if (__builtin_amdgcn_ballot_w64(mx - mrun > 8.0f) != 0ull) {
;         const float alpha = fast_exp2(mrun - mnew);
;         lrun *= alpha;
;         for (int i = 0; i < 16; ++i) { o0[i] *= alpha; o1[i] *= alpha; }
;         mrun = mnew;
;       }
.LBB0_915:
	s_or_b64 exec, exec, s[24:25]
	v_max_f32_e32 v0, v83, v83
	v_max_f32_e32 v182, v82, v82
	v_max_f32_e32 v0, v182, v0
	v_max3_f32 v0, v0, v84, v85
	v_max3_f32 v0, v0, v86, v87
	v_max3_f32 v0, v0, v88, v89
	v_max3_f32 v0, v0, v90, v91
	v_max3_f32 v0, v0, v92, v93
	v_max3_f32 v0, v0, v94, v95
	v_max3_f32 v0, v0, v96, v97
	v_max3_f32 v0, v0, v66, v67
	v_max3_f32 v0, v0, v68, v69
	v_max3_f32 v0, v0, v70, v71
	v_max3_f32 v0, v0, v72, v73
	v_max3_f32 v0, v0, v74, v75
	v_max3_f32 v0, v0, v76, v77
	v_max3_f32 v0, v0, v78, v79
	v_max3_f32 v0, v0, v80, v81
	v_max3_f32 v0, v0, v50, v51
	v_max3_f32 v0, v0, v52, v53
	v_max3_f32 v0, v0, v54, v55
	v_max3_f32 v0, v0, v56, v57
	v_max3_f32 v0, v0, v58, v59
	v_max3_f32 v0, v0, v60, v61
	v_max3_f32 v0, v0, v62, v63
	v_max3_f32 v0, v0, v64, v65
	v_max3_f32 v0, v0, v34, v35
	v_max3_f32 v0, v0, v36, v37
	v_max3_f32 v0, v0, v38, v39
	v_max3_f32 v0, v0, v40, v41
	v_and_b32_e32 v183, 64, v186
	v_max3_f32 v0, v0, v42, v43
	v_xor_b32_e32 v182, 32, v186
	v_add_u32_e32 v183, 64, v183
	v_max3_f32 v0, v0, v44, v45
	v_cmp_lt_i32_e32 vcc, v182, v183
	v_max3_f32 v0, v0, v46, v47
	v_max3_f32 v0, v0, v48, v49
	v_cndmask_b32_e32 v182, v186, v182, vcc
	v_lshlrev_b32_e32 v182, 2, v182
	v_mov_b32_e32 v182, v0
	s_nop 1
	v_permlane32_swap_b32_e32 v182, v0
	s_mov_b32 s24, 0x41000000
	s_waitcnt lgkmcnt(0)
	v_max_f32_e32 v182, v182, v182
	v_max_f32_e32 v0, v0, v182
	v_sub_f32_e32 v182, v0, v204
	v_cmp_lt_f32_e32 vcc, s24, v182
	s_cbranch_vccz .LBB0_917
	v_max_f32_e32 v0, v0, v0
	v_max_f32_e32 v182, v204, v204
	v_max_f32_e32 v182, v182, v0
	v_sub_f32_e32 v0, v204, v182
	v_exp_f32_e32 v0, v0
	v_mov_b32_e32 v204, v182
	v_pk_mul_f32 v[32:33], v[32:33], v[0:1] op_sel_hi:[1,0]
	v_pk_mul_f32 v[30:31], v[30:31], v[0:1] op_sel_hi:[1,0]
	v_pk_mul_f32 v[28:29], v[28:29], v[0:1] op_sel_hi:[1,0]
	v_pk_mul_f32 v[26:27], v[26:27], v[0:1] op_sel_hi:[1,0]
	v_pk_mul_f32 v[24:25], v[24:25], v[0:1] op_sel_hi:[1,0]
	v_pk_mul_f32 v[22:23], v[22:23], v[0:1] op_sel_hi:[1,0]
	v_pk_mul_f32 v[20:21], v[20:21], v[0:1] op_sel_hi:[1,0]
	v_pk_mul_f32 v[18:19], v[18:19], v[0:1] op_sel_hi:[1,0]
	v_pk_mul_f32 v[16:17], v[16:17], v[0:1] op_sel_hi:[1,0]
	v_pk_mul_f32 v[14:15], v[14:15], v[0:1] op_sel_hi:[1,0]
	v_pk_mul_f32 v[12:13], v[12:13], v[0:1] op_sel_hi:[1,0]
	v_pk_mul_f32 v[10:11], v[10:11], v[0:1] op_sel_hi:[1,0]
	v_pk_mul_f32 v[8:9], v[8:9], v[0:1] op_sel_hi:[1,0]
	v_pk_mul_f32 v[6:7], v[6:7], v[0:1] op_sel_hi:[1,0]
	v_pk_mul_f32 v[4:5], v[4:5], v[0:1] op_sel_hi:[1,0]
	v_pk_mul_f32 v[2:3], v[2:3], v[0:1] op_sel_hi:[1,0]
	v_mul_f32_e32 v203, v203, v0

; #define MFMA32(a, b, c) __builtin_amdgcn_mfma_f32_32x32x16_bf16((a), (b), (c), 0, 0, 0)
;     ...
;     f32x16 sc;
;     for (int i = 0; i < 16; ++i) sc[i] = 0.f;
;     {
;       const bf16x8* fb = (const bf16x8*)(smem + DS_QBAR);
;       #pragma unroll
;       for (int s = 0; s < 4; ++s) sc = MFMA32(a[s], fb[s * 64 + lane], sc);
;       for (int i = 0; i < 16; ++i) sc[i] *= 0.5f;
;     }
;     #pragma unroll
;     for (int hd = 0; hd < 8; ++hd) {
;       f32x16 acc;
;       for (int i = 0; i < 16; ++i) acc[i] = 0.f;
;       #pragma unroll
;       for (int s = 0; s < 4; ++s) acc = MFMA32(a[s], fq[(hd * 4 + s) * 64 + lane], acc);
;       for (int i = 0; i < 16; ++i) sc[i] = fmaf(wv[hd], __builtin_fabsf(acc[i]), sc[i]);
;     }
.Lhf_nopf:
	ds_read_b128 v[66:69], v199 offset:45056
	ds_read_b128 v[70:73], v199 offset:46080
	ds_read_b128 v[74:77], v199 offset:47104
	ds_read_b128 v[78:81], v199 offset:48128
	v_mfma_f32_32x32x16_bf16 v[2:17], v[130:133], v[100:103], 0
	v_mfma_f32_32x32x16_bf16 v[2:17], v[162:165], v[104:107], v[2:17]
	v_mfma_f32_32x32x16_bf16 v[2:17], v[166:169], v[108:111], v[2:17]
	v_mfma_f32_32x32x16_bf16 v[2:17], v[170:173], v[112:115], v[2:17]
	v_mfma_f32_32x32x16_bf16 v[18:33], v[130:133], v[116:119], 0
	v_mfma_f32_32x32x16_bf16 v[18:33], v[162:165], v[120:123], v[18:33]
	v_mfma_f32_32x32x16_bf16 v[18:33], v[166:169], v[124:127], v[18:33]
	v_mfma_f32_32x32x16_bf16 v[18:33], v[170:173], v[208:211], v[18:33]
	v_mfma_f32_32x32x16_bf16 v[34:49], v[130:133], v[212:215], 0
	v_mul_f32_e32 v50, 0.5, v2
	v_mul_f32_e32 v51, 0.5, v3
	v_mul_f32_e32 v52, 0.5, v4
	v_mul_f32_e32 v53, 0.5, v5
	v_mfma_f32_32x32x16_bf16 v[34:49], v[162:165], v[216:219], v[34:49]
	v_mul_f32_e32 v54, 0.5, v6
	v_mul_f32_e32 v55, 0.5, v7
	v_mul_f32_e32 v56, 0.5, v8
	v_mul_f32_e32 v57, 0.5, v9
	v_mfma_f32_32x32x16_bf16 v[34:49], v[166:169], v[220:223], v[34:49]
	v_mul_f32_e32 v58, 0.5, v10
	v_mul_f32_e32 v59, 0.5, v11
	v_mul_f32_e32 v60, 0.5, v12
	v_mul_f32_e32 v61, 0.5, v13
	v_mfma_f32_32x32x16_bf16 v[34:49], v[170:173], v[224:227], v[34:49]
	v_mul_f32_e32 v62, 0.5, v14
	v_mul_f32_e32 v63, 0.5, v15
	v_mul_f32_e32 v64, 0.5, v16
	v_mul_f32_e32 v65, 0.5, v17
	v_mfma_f32_32x32x16_bf16 v[2:17], v[130:133], v[228:231], 0
	v_fma_f32 v50, v190, |v18|, v50
	v_fma_f32 v51, v190, |v19|, v51
	v_fma_f32 v52, v190, |v20|, v52
	v_fma_f32 v53, v190, |v21|, v53
	v_mfma_f32_32x32x16_bf16 v[2:17], v[162:165], v[232:235], v[2:17]
	v_fma_f32 v54, v190, |v22|, v54
	v_fma_f32 v55, v190, |v23|, v55
	v_fma_f32 v56, v190, |v24|, v56
	v_fma_f32 v57, v190, |v25|, v57
	v_mfma_f32_32x32x16_bf16 v[2:17], v[166:169], v[236:239], v[2:17]
	v_fma_f32 v58, v190, |v26|, v58
	v_fma_f32 v59, v190, |v27|, v59
	v_fma_f32 v60, v190, |v28|, v60
	v_fma_f32 v61, v190, |v29|, v61
	v_mfma_f32_32x32x16_bf16 v[2:17], v[170:173], v[240:243], v[2:17]
	v_fma_f32 v62, v190, |v30|, v62
	v_fma_f32 v63, v190, |v31|, v63
	v_fma_f32 v64, v190, |v32|, v64
	v_fma_f32 v65, v190, |v33|, v65
	s_waitcnt lgkmcnt(3)
	v_mfma_f32_32x32x16_bf16 v[18:33], v[130:133], v[66:69], 0
	ds_read_b128 v[66:69], v199 offset:49152
	v_fma_f32 v50, v191, |v34|, v50
	v_fma_f32 v51, v191, |v35|, v51
	v_fma_f32 v52, v191, |v36|, v52
	v_fma_f32 v53, v191, |v37|, v53
	s_waitcnt lgkmcnt(3)
	v_mfma_f32_32x32x16_bf16 v[18:33], v[162:165], v[70:73], v[18:33]
	ds_read_b128 v[70:73], v199 offset:50176
	v_fma_f32 v54, v191, |v38|, v54
	v_fma_f32 v55, v191, |v39|, v55
	v_fma_f32 v56, v191, |v40|, v56
	v_fma_f32 v57, v191, |v41|, v57
	s_waitcnt lgkmcnt(3)
	v_mfma_f32_32x32x16_bf16 v[18:33], v[166:169], v[74:77], v[18:33]
	ds_read_b128 v[74:77], v199 offset:51200
	v_fma_f32 v58, v191, |v42|, v58
	v_fma_f32 v59, v191, |v43|, v59
	v_fma_f32 v60, v191, |v44|, v60
	v_fma_f32 v61, v191, |v45|, v61
	s_waitcnt lgkmcnt(3)
	v_mfma_f32_32x32x16_bf16 v[18:33], v[170:173], v[78:81], v[18:33]
	ds_read_b128 v[78:81], v199 offset:52224
	v_fma_f32 v62, v191, |v46|, v62
	v_fma_f32 v63, v191, |v47|, v63
	v_fma_f32 v64, v191, |v48|, v64
	v_fma_f32 v65, v191, |v49|, v65
	s_waitcnt lgkmcnt(3)
	v_mfma_f32_32x32x16_bf16 v[34:49], v[130:133], v[66:69], 0
	ds_read_b128 v[66:69], v199 offset:53248
	v_fma_f32 v50, v192, |v2|, v50
	v_fma_f32 v51, v192, |v3|, v51
	v_fma_f32 v52, v192, |v4|, v52
	v_fma_f32 v53, v192, |v5|, v53
	s_waitcnt lgkmcnt(3)
	v_mfma_f32_32x32x16_bf16 v[34:49], v[162:165], v[70:73], v[34:49]
	ds_read_b128 v[70:73], v199 offset:54272
	v_fma_f32 v54, v192, |v6|, v54
	v_fma_f32 v55, v192, |v7|, v55
	v_fma_f32 v56, v192, |v8|, v56
	v_fma_f32 v57, v192, |v9|, v57
	s_waitcnt lgkmcnt(3)
	v_mfma_f32_32x32x16_bf16 v[34:49], v[166:169], v[74:77], v[34:49]
	ds_read_b128 v[74:77], v199 offset:55296
	v_fma_f32 v58, v192, |v10|, v58
	v_fma_f32 v59, v192, |v11|, v59
	v_fma_f32 v60, v192, |v12|, v60
	v_fma_f32 v61, v192, |v13|, v61
	s_waitcnt lgkmcnt(3)
	v_mfma_f32_32x32x16_bf16 v[34:49], v[170:173], v[78:81], v[34:49]
	ds_read_b128 v[78:81], v199 offset:56320
	v_fma_f32 v62, v192, |v14|, v62
	v_fma_f32 v63, v192, |v15|, v63
	v_fma_f32 v64, v192, |v16|, v64
	v_fma_f32 v65, v192, |v17|, v65
	s_waitcnt lgkmcnt(3)
	v_mfma_f32_32x32x16_bf16 v[2:17], v[130:133], v[66:69], 0
	ds_read_b128 v[66:69], v199 offset:57344
	v_fma_f32 v50, v193, |v18|, v50
	v_fma_f32 v51, v193, |v19|, v51
	v_fma_f32 v52, v193, |v20|, v52
	v_fma_f32 v53, v193, |v21|, v53
	s_waitcnt lgkmcnt(3)
	v_mfma_f32_32x32x16_bf16 v[2:17], v[162:165], v[70:73], v[2:17]
	ds_read_b128 v[70:73], v199 offset:58368
	v_fma_f32 v54, v193, |v22|, v54
	v_fma_f32 v55, v193, |v23|, v55
	v_fma_f32 v56, v193, |v24|, v56
	v_fma_f32 v57, v193, |v25|, v57
	s_waitcnt lgkmcnt(3)
	v_mfma_f32_32x32x16_bf16 v[2:17], v[166:169], v[74:77], v[2:17]
	ds_read_b128 v[74:77], v199 offset:59392
	v_fma_f32 v58, v193, |v26|, v58
	v_fma_f32 v59, v193, |v27|, v59
	v_fma_f32 v60, v193, |v28|, v60
	v_fma_f32 v61, v193, |v29|, v61
	s_waitcnt lgkmcnt(3)
	v_mfma_f32_32x32x16_bf16 v[2:17], v[170:173], v[78:81], v[2:17]
	ds_read_b128 v[78:81], v199 offset:60416
	v_fma_f32 v62, v193, |v30|, v62
	v_fma_f32 v63, v193, |v31|, v63
	v_fma_f32 v64, v193, |v32|, v64
	v_fma_f32 v65, v193, |v33|, v65
	s_waitcnt lgkmcnt(3)
	v_mfma_f32_32x32x16_bf16 v[18:33], v[130:133], v[66:69], 0
	ds_read_b128 v[66:69], v199 offset:61440
	v_fma_f32 v50, v194, |v34|, v50
	v_fma_f32 v51, v194, |v35|, v51
	v_fma_f32 v52, v194, |v36|, v52
	v_fma_f32 v53, v194, |v37|, v53
	s_waitcnt lgkmcnt(3)
; DI int crow(int reg, int h) { return (reg & 3) + 8 * (reg >> 2) + 4 * h; }
; #define MFMA32(a, b, c) __builtin_amdgcn_mfma_f32_32x32x16_bf16((a), (b), (c), 0, 0, 0)
;     ...
;   for (; kt < nt; kt += stride) {
;     const bool more = kt + stride < nt;
;     if (more) for (int s = 0; s < 4; ++s) an[s] = ldg<bf16x8>(Ikb + (size_t)((kt + stride) * 32 + r) * 64 + 16 * s + 8 * hh);
;     f32x16 sc;
;     for (int i = 0; i < 16; ++i) sc[i] = 0.f;
;     {
;       const bf16x8* fb = (const bf16x8*)(smem + DS_QBAR);
;       #pragma unroll
;       for (int s = 0; s < 4; ++s) sc = MFMA32(a[s], fb[s * 64 + lane], sc);
;       for (int i = 0; i < 16; ++i) sc[i] *= 0.5f;
;     }
;     #pragma unroll
;     for (int hd = 0; hd < 8; ++hd) {
;       f32x16 acc;
;       for (int i = 0; i < 16; ++i) acc[i] = 0.f;
;       #pragma unroll
;       for (int s = 0; s < 4; ++s) acc = MFMA32(a[s], fq[(hd * 4 + s) * 64 + lane], acc);
;       for (int i = 0; i < 16; ++i) sc[i] = fmaf(wv[hd], __builtin_fabsf(acc[i]), sc[i]);
;     }
;     f(sc, kt);
;     if (more) for (int s = 0; s < 4; ++s) a[s] = an[s];
;   }
; DI void dsa_item(const Params& p, int b, int blk) {
;     ...
;     auto binof = [&](float s) -> unsigned { return (unsigned)(int)fminf(fmaxf(__fmul_rn(__fsub_rn(s, b_lo), b_sc), 0.f), 255.f); };
;     score_pass(Ikb, wv, nt, w, lane, [&](const f32x16& sc, int kt) {
;       for (int i = 0; i < 16; ++i) {
;         int key = kt * 32 + crow(i, hh);
;         if (key <= qpos) atomicAdd(&hist[binof(sc[i]) * 32 + r], 1u);
;       }
;     });
	v_mfma_f32_32x32x16_bf16 v[18:33], v[162:165], v[70:73], v[18:33]
	ds_read_b128 v[70:73], v199 offset:62464
	v_fma_f32 v54, v194, |v38|, v54
	v_fma_f32 v55, v194, |v39|, v55
	v_fma_f32 v56, v194, |v40|, v56
	v_fma_f32 v57, v194, |v41|, v57
	s_waitcnt lgkmcnt(3)
	v_mfma_f32_32x32x16_bf16 v[18:33], v[166:169], v[74:77], v[18:33]
	ds_read_b128 v[74:77], v199 offset:63488
	v_fma_f32 v58, v194, |v42|, v58
	v_fma_f32 v59, v194, |v43|, v59
	v_fma_f32 v60, v194, |v44|, v60
	v_fma_f32 v61, v194, |v45|, v61
	s_waitcnt lgkmcnt(3)
	v_mfma_f32_32x32x16_bf16 v[18:33], v[170:173], v[78:81], v[18:33]
	ds_read_b128 v[78:81], v199 offset:64512
	v_fma_f32 v62, v194, |v46|, v62
	v_fma_f32 v63, v194, |v47|, v63
	v_fma_f32 v64, v194, |v48|, v64
	v_fma_f32 v65, v194, |v49|, v65
	s_waitcnt lgkmcnt(3)
	v_mfma_f32_32x32x16_bf16 v[34:49], v[130:133], v[66:69], 0
	v_fma_f32 v50, v195, |v2|, v50
	v_fma_f32 v51, v195, |v3|, v51
	v_fma_f32 v52, v195, |v4|, v52
	v_fma_f32 v53, v195, |v5|, v53
	s_waitcnt lgkmcnt(2)
	v_mfma_f32_32x32x16_bf16 v[34:49], v[162:165], v[70:73], v[34:49]
	v_fma_f32 v54, v195, |v6|, v54
	v_fma_f32 v55, v195, |v7|, v55
	v_fma_f32 v56, v195, |v8|, v56
	v_fma_f32 v57, v195, |v9|, v57
	s_waitcnt lgkmcnt(1)
	v_mfma_f32_32x32x16_bf16 v[34:49], v[166:169], v[74:77], v[34:49]
	v_fma_f32 v58, v195, |v10|, v58
	v_fma_f32 v59, v195, |v11|, v59
	v_fma_f32 v60, v195, |v12|, v60
	v_fma_f32 v61, v195, |v13|, v61
	s_waitcnt lgkmcnt(0)
	v_mfma_f32_32x32x16_bf16 v[34:49], v[170:173], v[78:81], v[34:49]
	v_fma_f32 v62, v195, |v14|, v62
	v_fma_f32 v63, v195, |v15|, v63
	v_fma_f32 v64, v195, |v16|, v64
	v_fma_f32 v65, v195, |v17|, v65
	v_fma_f32 v50, v196, |v18|, v50
	v_fma_f32 v51, v196, |v19|, v51
	v_fma_f32 v52, v196, |v20|, v52
	v_fma_f32 v53, v196, |v21|, v53
	v_fma_f32 v54, v196, |v22|, v54
	v_fma_f32 v55, v196, |v23|, v55
	v_fma_f32 v56, v196, |v24|, v56
	v_fma_f32 v57, v196, |v25|, v57
	v_fma_f32 v58, v196, |v26|, v58
	v_fma_f32 v59, v196, |v27|, v59
	v_fma_f32 v60, v196, |v28|, v60
	v_fma_f32 v61, v196, |v29|, v61
	v_fma_f32 v62, v196, |v30|, v62
	v_fma_f32 v63, v196, |v31|, v63
	v_fma_f32 v64, v196, |v32|, v64
	v_fma_f32 v65, v196, |v33|, v65
	v_fma_f32 v50, v197, |v34|, v50
	v_fma_f32 v51, v197, |v35|, v51
	v_fma_f32 v52, v197, |v36|, v52
	v_fma_f32 v53, v197, |v37|, v53
	v_fma_f32 v54, v197, |v38|, v54
	v_fma_f32 v55, v197, |v39|, v55
	v_fma_f32 v56, v197, |v40|, v56
	v_fma_f32 v57, v197, |v41|, v57
	v_fma_f32 v58, v197, |v42|, v58
	v_fma_f32 v59, v197, |v43|, v59
	v_fma_f32 v60, v197, |v44|, v60
	v_fma_f32 v61, v197, |v45|, v61
	v_fma_f32 v62, v197, |v46|, v62
	v_fma_f32 v63, v197, |v47|, v63
	v_fma_f32 v64, v197, |v48|, v64
	v_fma_f32 v65, v197, |v49|, v65
	v_sub_f32_e32 v82, v50, v177
	v_sub_f32_e32 v83, v51, v177
	v_sub_f32_e32 v84, v52, v177
	v_sub_f32_e32 v85, v53, v177
	v_sub_f32_e32 v86, v54, v177
	v_sub_f32_e32 v87, v55, v177
	v_sub_f32_e32 v88, v56, v177
	v_sub_f32_e32 v89, v57, v177
	v_sub_f32_e32 v90, v58, v177
	v_sub_f32_e32 v91, v59, v177
	v_sub_f32_e32 v92, v60, v177
	v_sub_f32_e32 v93, v61, v177
	v_sub_f32_e32 v94, v62, v177
	v_sub_f32_e32 v95, v63, v177
	v_sub_f32_e32 v96, v64, v177
	v_sub_f32_e32 v97, v65, v177
	v_mul_f32_e32 v82, v206, v82
	v_mul_f32_e32 v83, v206, v83
	v_mul_f32_e32 v84, v206, v84
	v_mul_f32_e32 v85, v206, v85
	v_mul_f32_e32 v86, v206, v86
	v_mul_f32_e32 v87, v206, v87
	v_mul_f32_e32 v88, v206, v88
	v_mul_f32_e32 v89, v206, v89
	v_mul_f32_e32 v90, v206, v90
	v_mul_f32_e32 v91, v206, v91
	v_mul_f32_e32 v92, v206, v92
	v_mul_f32_e32 v93, v206, v93
	v_mul_f32_e32 v94, v206, v94
	v_mul_f32_e32 v95, v206, v95
	v_mul_f32_e32 v96, v206, v96
	v_mul_f32_e32 v97, v206, v97
	s_mov_b32 vcc_hi, 0x437f0000
	v_med3_f32 v82, v82, 0, vcc_hi
	v_med3_f32 v83, v83, 0, vcc_hi
	v_med3_f32 v84, v84, 0, vcc_hi
	v_med3_f32 v85, v85, 0, vcc_hi
	v_med3_f32 v86, v86, 0, vcc_hi
	v_med3_f32 v87, v87, 0, vcc_hi
	v_med3_f32 v88, v88, 0, vcc_hi
	v_med3_f32 v89, v89, 0, vcc_hi
	v_med3_f32 v90, v90, 0, vcc_hi
	v_med3_f32 v91, v91, 0, vcc_hi
	v_med3_f32 v92, v92, 0, vcc_hi
	v_med3_f32 v93, v93, 0, vcc_hi
	v_med3_f32 v94, v94, 0, vcc_hi
	v_med3_f32 v95, v95, 0, vcc_hi
	v_med3_f32 v96, v96, 0, vcc_hi
	v_med3_f32 v97, v97, 0, vcc_hi
	v_cvt_i32_f32_e32 v82, v82
	v_cvt_i32_f32_e32 v83, v83
	v_cvt_i32_f32_e32 v84, v84
	v_cvt_i32_f32_e32 v85, v85
	v_cvt_i32_f32_e32 v86, v86
	v_cvt_i32_f32_e32 v87, v87
	v_cvt_i32_f32_e32 v88, v88
	v_cvt_i32_f32_e32 v89, v89
	v_cvt_i32_f32_e32 v90, v90
	v_cvt_i32_f32_e32 v91, v91
	v_cvt_i32_f32_e32 v92, v92
	v_cvt_i32_f32_e32 v93, v93
	v_cvt_i32_f32_e32 v94, v94
	v_cvt_i32_f32_e32 v95, v95
	v_cvt_i32_f32_e32 v96, v96
	v_cvt_i32_f32_e32 v97, v97
	v_lshl_add_u32 v82, v82, 7, v205
	v_lshl_add_u32 v83, v83, 7, v205
	v_lshl_add_u32 v84, v84, 7, v205
	v_lshl_add_u32 v85, v85, 7, v205
	v_lshl_add_u32 v86, v86, 7, v205
	v_lshl_add_u32 v87, v87, 7, v205
	v_lshl_add_u32 v88, v88, 7, v205
	v_lshl_add_u32 v89, v89, 7, v205
	v_lshl_add_u32 v90, v90, 7, v205
	v_lshl_add_u32 v91, v91, 7, v205
	v_lshl_add_u32 v92, v92, 7, v205
	v_lshl_add_u32 v93, v93, 7, v205
	v_lshl_add_u32 v94, v94, 7, v205
	v_lshl_add_u32 v95, v95, 7, v205
	v_lshl_add_u32 v96, v96, 7, v205
	v_lshl_add_u32 v97, v97, 7, v205
	ds_add_u32 v82, v179
	ds_add_u32 v83, v179
	ds_add_u32 v84, v179
	ds_add_u32 v85, v179
	ds_add_u32 v86, v179
	ds_add_u32 v87, v179
	ds_add_u32 v88, v179
	ds_add_u32 v89, v179
	ds_add_u32 v90, v179
	ds_add_u32 v91, v179
	ds_add_u32 v92, v179
	ds_add_u32 v93, v179
	ds_add_u32 v94, v179
	ds_add_u32 v95, v179
	ds_add_u32 v96, v179
	ds_add_u32 v97, v179
	s_waitcnt vmcnt(0)
	v_mov_b32_e32 v130, v158
	v_mov_b32_e32 v131, v159
	v_mov_b32_e32 v132, v160
	v_mov_b32_e32 v133, v161
	v_mov_b32_e32 v162, v154
	v_mov_b32_e32 v163, v155
	v_mov_b32_e32 v164, v156
	v_mov_b32_e32 v165, v157
	v_mov_b32_e32 v166, v150
	v_mov_b32_e32 v167, v151
	v_mov_b32_e32 v168, v152
	v_mov_b32_e32 v169, v153
	v_mov_b32_e32 v170, v146
	v_mov_b32_e32 v171, v147
	v_mov_b32_e32 v172, v148
	v_mov_b32_e32 v173, v149
	v_add_u32_e32 v176, 0x100, v176
	v_add_u32_e32 v207, 8, v207
	s_mov_b32 s100, s101
	s_cmp_le_i32 s100, s37
	s_cbranch_scc1 .Lhf_top
	s_branch .LBB0_990

; #define MFMA32(a, b, c) __builtin_amdgcn_mfma_f32_32x32x16_bf16((a), (b), (c), 0, 0, 0)
;     ...
;     f32x16 sc;
;     for (int i = 0; i < 16; ++i) sc[i] = 0.f;
;     {
;       const bf16x8* fb = (const bf16x8*)(smem + DS_QBAR);
;       #pragma unroll
;       for (int s = 0; s < 4; ++s) sc = MFMA32(a[s], fb[s * 64 + lane], sc);
;       for (int i = 0; i < 16; ++i) sc[i] *= 0.5f;
;     }
;     #pragma unroll
;     for (int hd = 0; hd < 8; ++hd) {
;       f32x16 acc;
;       for (int i = 0; i < 16; ++i) acc[i] = 0.f;
;       #pragma unroll
;       for (int s = 0; s < 4; ++s) acc = MFMA32(a[s], fq[(hd * 4 + s) * 64 + lane], acc);
;       for (int i = 0; i < 16; ++i) sc[i] = fmaf(wv[hd], __builtin_fabsf(acc[i]), sc[i]);
;     }
.Lcf_nopf:
	ds_read_b128 v[66:69], v199 offset:40960
	ds_read_b128 v[70:73], v199 offset:41984
	ds_read_b128 v[74:77], v199 offset:43008
	ds_read_b128 v[78:81], v199 offset:44032
	v_mfma_f32_32x32x16_bf16 v[2:17], v[130:133], v[100:103], 0
	v_mfma_f32_32x32x16_bf16 v[2:17], v[162:165], v[104:107], v[2:17]
	v_mfma_f32_32x32x16_bf16 v[2:17], v[166:169], v[108:111], v[2:17]
	v_mfma_f32_32x32x16_bf16 v[2:17], v[170:173], v[112:115], v[2:17]
	v_mfma_f32_32x32x16_bf16 v[18:33], v[130:133], v[116:119], 0
	v_mfma_f32_32x32x16_bf16 v[18:33], v[162:165], v[120:123], v[18:33]
	v_mfma_f32_32x32x16_bf16 v[18:33], v[166:169], v[124:127], v[18:33]
	v_mfma_f32_32x32x16_bf16 v[18:33], v[170:173], v[230:233], v[18:33]
	v_mfma_f32_32x32x16_bf16 v[34:49], v[130:133], v[234:237], 0
	v_mul_f32_e32 v50, 0.5, v2
	v_mul_f32_e32 v51, 0.5, v3
	v_mul_f32_e32 v52, 0.5, v4
	v_mul_f32_e32 v53, 0.5, v5
	v_mfma_f32_32x32x16_bf16 v[34:49], v[162:165], v[240:243], v[34:49]
	v_mul_f32_e32 v54, 0.5, v6
	v_mul_f32_e32 v55, 0.5, v7
	v_mul_f32_e32 v56, 0.5, v8
	v_mul_f32_e32 v57, 0.5, v9
	v_mfma_f32_32x32x16_bf16 v[34:49], v[166:169], v[244:247], v[34:49]
	v_mul_f32_e32 v58, 0.5, v10
	v_mul_f32_e32 v59, 0.5, v11
	v_mul_f32_e32 v60, 0.5, v12
	v_mul_f32_e32 v61, 0.5, v13
	v_mfma_f32_32x32x16_bf16 v[34:49], v[170:173], v[248:251], v[34:49]
	v_mul_f32_e32 v62, 0.5, v14
	v_mul_f32_e32 v63, 0.5, v15
	v_mul_f32_e32 v64, 0.5, v16
	v_mul_f32_e32 v65, 0.5, v17
	s_waitcnt lgkmcnt(3)
	v_mfma_f32_32x32x16_bf16 v[2:17], v[130:133], v[66:69], 0
	ds_read_b128 v[66:69], v199 offset:45056
	v_fma_f32 v50, v190, |v18|, v50
	v_fma_f32 v51, v190, |v19|, v51
	v_fma_f32 v52, v190, |v20|, v52
	v_fma_f32 v53, v190, |v21|, v53
	s_waitcnt lgkmcnt(3)
	v_mfma_f32_32x32x16_bf16 v[2:17], v[162:165], v[70:73], v[2:17]
	ds_read_b128 v[70:73], v199 offset:46080
	v_fma_f32 v54, v190, |v22|, v54
	v_fma_f32 v55, v190, |v23|, v55
	v_fma_f32 v56, v190, |v24|, v56
	v_fma_f32 v57, v190, |v25|, v57
	s_waitcnt lgkmcnt(3)
	v_mfma_f32_32x32x16_bf16 v[2:17], v[166:169], v[74:77], v[2:17]
	ds_read_b128 v[74:77], v199 offset:47104
	v_fma_f32 v58, v190, |v26|, v58
	v_fma_f32 v59, v190, |v27|, v59
	v_fma_f32 v60, v190, |v28|, v60
	v_fma_f32 v61, v190, |v29|, v61
	s_waitcnt lgkmcnt(3)
	v_mfma_f32_32x32x16_bf16 v[2:17], v[170:173], v[78:81], v[2:17]
	ds_read_b128 v[78:81], v199 offset:48128
	v_fma_f32 v62, v190, |v30|, v62
	v_fma_f32 v63, v190, |v31|, v63
	v_fma_f32 v64, v190, |v32|, v64
	v_fma_f32 v65, v190, |v33|, v65
	s_waitcnt lgkmcnt(3)
	v_mfma_f32_32x32x16_bf16 v[18:33], v[130:133], v[66:69], 0
	ds_read_b128 v[66:69], v199 offset:49152
	v_fma_f32 v50, v191, |v34|, v50
	v_fma_f32 v51, v191, |v35|, v51
	v_fma_f32 v52, v191, |v36|, v52
	v_fma_f32 v53, v191, |v37|, v53
	s_waitcnt lgkmcnt(3)
	v_mfma_f32_32x32x16_bf16 v[18:33], v[162:165], v[70:73], v[18:33]
	ds_read_b128 v[70:73], v199 offset:50176
	v_fma_f32 v54, v191, |v38|, v54
	v_fma_f32 v55, v191, |v39|, v55
	v_fma_f32 v56, v191, |v40|, v56
	v_fma_f32 v57, v191, |v41|, v57
	s_waitcnt lgkmcnt(3)
	v_mfma_f32_32x32x16_bf16 v[18:33], v[166:169], v[74:77], v[18:33]
	ds_read_b128 v[74:77], v199 offset:51200
	v_fma_f32 v58, v191, |v42|, v58
	v_fma_f32 v59, v191, |v43|, v59
	v_fma_f32 v60, v191, |v44|, v60
	v_fma_f32 v61, v191, |v45|, v61
	s_waitcnt lgkmcnt(3)
	v_mfma_f32_32x32x16_bf16 v[18:33], v[170:173], v[78:81], v[18:33]
	ds_read_b128 v[78:81], v199 offset:52224
	v_fma_f32 v62, v191, |v46|, v62
	v_fma_f32 v63, v191, |v47|, v63
	v_fma_f32 v64, v191, |v48|, v64
	v_fma_f32 v65, v191, |v49|, v65
	s_waitcnt lgkmcnt(3)
	v_mfma_f32_32x32x16_bf16 v[34:49], v[130:133], v[66:69], 0
	ds_read_b128 v[66:69], v199 offset:53248
	v_fma_f32 v50, v192, |v2|, v50
	v_fma_f32 v51, v192, |v3|, v51
	v_fma_f32 v52, v192, |v4|, v52
	v_fma_f32 v53, v192, |v5|, v53
	s_waitcnt lgkmcnt(3)
	v_mfma_f32_32x32x16_bf16 v[34:49], v[162:165], v[70:73], v[34:49]
	ds_read_b128 v[70:73], v199 offset:54272
	v_fma_f32 v54, v192, |v6|, v54
	v_fma_f32 v55, v192, |v7|, v55
	v_fma_f32 v56, v192, |v8|, v56
	v_fma_f32 v57, v192, |v9|, v57
	s_waitcnt lgkmcnt(3)
	v_mfma_f32_32x32x16_bf16 v[34:49], v[166:169], v[74:77], v[34:49]
	ds_read_b128 v[74:77], v199 offset:55296
	v_fma_f32 v58, v192, |v10|, v58
	v_fma_f32 v59, v192, |v11|, v59
	v_fma_f32 v60, v192, |v12|, v60
	v_fma_f32 v61, v192, |v13|, v61
	s_waitcnt lgkmcnt(3)
	v_mfma_f32_32x32x16_bf16 v[34:49], v[170:173], v[78:81], v[34:49]
	ds_read_b128 v[78:81], v199 offset:56320
	v_fma_f32 v62, v192, |v14|, v62
	v_fma_f32 v63, v192, |v15|, v63
	v_fma_f32 v64, v192, |v16|, v64
	v_fma_f32 v65, v192, |v17|, v65
	s_waitcnt lgkmcnt(3)
	v_mfma_f32_32x32x16_bf16 v[2:17], v[130:133], v[66:69], 0
	ds_read_b128 v[66:69], v199 offset:57344
	v_fma_f32 v50, v193, |v18|, v50
	v_fma_f32 v51, v193, |v19|, v51
	v_fma_f32 v52, v193, |v20|, v52
	v_fma_f32 v53, v193, |v21|, v53
	s_waitcnt lgkmcnt(3)
	v_mfma_f32_32x32x16_bf16 v[2:17], v[162:165], v[70:73], v[2:17]
	ds_read_b128 v[70:73], v199 offset:58368
	v_fma_f32 v54, v193, |v22|, v54
	v_fma_f32 v55, v193, |v23|, v55
	v_fma_f32 v56, v193, |v24|, v56
	v_fma_f32 v57, v193, |v25|, v57
	s_waitcnt lgkmcnt(3)
	v_mfma_f32_32x32x16_bf16 v[2:17], v[166:169], v[74:77], v[2:17]
	ds_read_b128 v[74:77], v199 offset:59392
	v_fma_f32 v58, v193, |v26|, v58
	v_fma_f32 v59, v193, |v27|, v59
	v_fma_f32 v60, v193, |v28|, v60
	v_fma_f32 v61, v193, |v29|, v61
	s_waitcnt lgkmcnt(3)
	v_mfma_f32_32x32x16_bf16 v[2:17], v[170:173], v[78:81], v[2:17]
	ds_read_b128 v[78:81], v199 offset:60416
	v_fma_f32 v62, v193, |v30|, v62
	v_fma_f32 v63, v193, |v31|, v63
	v_fma_f32 v64, v193, |v32|, v64
	v_fma_f32 v65, v193, |v33|, v65
	s_waitcnt lgkmcnt(3)
; DI int crow(int reg, int h) { return (reg & 3) + 8 * (reg >> 2) + 4 * h; }
; DI unsigned ordkey(float f) { unsigned u = __float_as_uint(f); return (u & 0x80000000u) ? ~u : (u | 0x80000000u); }
; DI void dsa_item(const Params& p, int b, int blk) {
;     ...
;     auto binof = [&](float s) -> unsigned { return (unsigned)(int)fminf(fmaxf(__fmul_rn(__fsub_rn(s, b_lo), b_sc), 0.f), 255.f); };
;     ...
;     {
;       const unsigned bstar = pf1[r];
;       score_pass(Ikb, wv, nt, w, lane, [&](const f32x16& sc, int kt) {
;         for (int i = 0; i < 16; ++i) {
;           int key = kt * 32 + crow(i, hh);
;           if (key <= qpos) {
;             const unsigned bn = binof(sc[i]);
;             if (bn > bstar) atomicOr(&mask[r * MASK_W + (key >> 5)], 1u << (key & 31));
;             else if (bn == bstar) { unsigned cp = atomicAdd(&candcnt[r], 1u); if (cp < CAND_CAP) cand[r * CAND_CAP + cp] = make_uint2(ordkey(sc[i]), (unsigned)key); }
;           }
;         }
;       });
	v_mfma_f32_32x32x16_bf16 v[18:33], v[130:133], v[66:69], 0
	ds_read_b128 v[66:69], v199 offset:61440
	v_fma_f32 v50, v194, |v34|, v50
	v_fma_f32 v51, v194, |v35|, v51
	v_fma_f32 v52, v194, |v36|, v52
	v_fma_f32 v53, v194, |v37|, v53
	s_waitcnt lgkmcnt(3)
	v_mfma_f32_32x32x16_bf16 v[18:33], v[162:165], v[70:73], v[18:33]
	ds_read_b128 v[70:73], v199 offset:62464
	v_fma_f32 v54, v194, |v38|, v54
	v_fma_f32 v55, v194, |v39|, v55
	v_fma_f32 v56, v194, |v40|, v56
	v_fma_f32 v57, v194, |v41|, v57
	s_waitcnt lgkmcnt(3)
	v_mfma_f32_32x32x16_bf16 v[18:33], v[166:169], v[74:77], v[18:33]
	ds_read_b128 v[74:77], v199 offset:63488
	v_fma_f32 v58, v194, |v42|, v58
	v_fma_f32 v59, v194, |v43|, v59
	v_fma_f32 v60, v194, |v44|, v60
	v_fma_f32 v61, v194, |v45|, v61
	s_waitcnt lgkmcnt(3)
	v_mfma_f32_32x32x16_bf16 v[18:33], v[170:173], v[78:81], v[18:33]
	ds_read_b128 v[78:81], v199 offset:64512
	v_fma_f32 v62, v194, |v46|, v62
	v_fma_f32 v63, v194, |v47|, v63
	v_fma_f32 v64, v194, |v48|, v64
	v_fma_f32 v65, v194, |v49|, v65
	s_waitcnt lgkmcnt(3)
	v_mfma_f32_32x32x16_bf16 v[34:49], v[130:133], v[66:69], 0
	v_fma_f32 v50, v195, |v2|, v50
	v_fma_f32 v51, v195, |v3|, v51
	v_fma_f32 v52, v195, |v4|, v52
	v_fma_f32 v53, v195, |v5|, v53
	s_waitcnt lgkmcnt(2)
	v_mfma_f32_32x32x16_bf16 v[34:49], v[162:165], v[70:73], v[34:49]
	v_fma_f32 v54, v195, |v6|, v54
	v_fma_f32 v55, v195, |v7|, v55
	v_fma_f32 v56, v195, |v8|, v56
	v_fma_f32 v57, v195, |v9|, v57
	s_waitcnt lgkmcnt(1)
	v_mfma_f32_32x32x16_bf16 v[34:49], v[166:169], v[74:77], v[34:49]
	v_fma_f32 v58, v195, |v10|, v58
	v_fma_f32 v59, v195, |v11|, v59
	v_fma_f32 v60, v195, |v12|, v60
	v_fma_f32 v61, v195, |v13|, v61
	s_waitcnt lgkmcnt(0)
	v_mfma_f32_32x32x16_bf16 v[34:49], v[170:173], v[78:81], v[34:49]
	v_fma_f32 v62, v195, |v14|, v62
	v_fma_f32 v63, v195, |v15|, v63
	v_fma_f32 v64, v195, |v16|, v64
	v_fma_f32 v65, v195, |v17|, v65
	v_fma_f32 v50, v196, |v18|, v50
	v_fma_f32 v51, v196, |v19|, v51
	v_fma_f32 v52, v196, |v20|, v52
	v_fma_f32 v53, v196, |v21|, v53
	v_fma_f32 v54, v196, |v22|, v54
	v_fma_f32 v55, v196, |v23|, v55
	v_fma_f32 v56, v196, |v24|, v56
	v_fma_f32 v57, v196, |v25|, v57
	v_fma_f32 v58, v196, |v26|, v58
	v_fma_f32 v59, v196, |v27|, v59
	v_fma_f32 v60, v196, |v28|, v60
	v_fma_f32 v61, v196, |v29|, v61
	v_fma_f32 v62, v196, |v30|, v62
	v_fma_f32 v63, v196, |v31|, v63
	v_fma_f32 v64, v196, |v32|, v64
	v_fma_f32 v65, v196, |v33|, v65
	v_fma_f32 v50, v197, |v34|, v50
	v_fma_f32 v51, v197, |v35|, v51
	v_fma_f32 v52, v197, |v36|, v52
	v_fma_f32 v53, v197, |v37|, v53
	v_fma_f32 v54, v197, |v38|, v54
	v_fma_f32 v55, v197, |v39|, v55
	v_fma_f32 v56, v197, |v40|, v56
	v_fma_f32 v57, v197, |v41|, v57
	v_fma_f32 v58, v197, |v42|, v58
	v_fma_f32 v59, v197, |v43|, v59
	v_fma_f32 v60, v197, |v44|, v60
	v_fma_f32 v61, v197, |v45|, v61
	v_fma_f32 v62, v197, |v46|, v62
	v_fma_f32 v63, v197, |v47|, v63
	v_fma_f32 v64, v197, |v48|, v64
	v_fma_f32 v65, v197, |v49|, v65
	v_sub_f32_e32 v82, v50, v177
	v_sub_f32_e32 v83, v51, v177
	v_sub_f32_e32 v84, v52, v177
	v_sub_f32_e32 v85, v53, v177
	v_sub_f32_e32 v86, v54, v177
	v_sub_f32_e32 v87, v55, v177
	v_sub_f32_e32 v88, v56, v177
	v_sub_f32_e32 v89, v57, v177
	v_sub_f32_e32 v90, v58, v177
	v_sub_f32_e32 v91, v59, v177
	v_sub_f32_e32 v92, v60, v177
	v_sub_f32_e32 v93, v61, v177
	v_sub_f32_e32 v94, v62, v177
	v_sub_f32_e32 v95, v63, v177
	v_sub_f32_e32 v96, v64, v177
	v_sub_f32_e32 v97, v65, v177
	v_mul_f32_e32 v82, v206, v82
	v_mul_f32_e32 v83, v206, v83
	v_mul_f32_e32 v84, v206, v84
	v_mul_f32_e32 v85, v206, v85
	v_mul_f32_e32 v86, v206, v86
	v_mul_f32_e32 v87, v206, v87
	v_mul_f32_e32 v88, v206, v88
	v_mul_f32_e32 v89, v206, v89
	v_mul_f32_e32 v90, v206, v90
	v_mul_f32_e32 v91, v206, v91
	v_mul_f32_e32 v92, v206, v92
	v_mul_f32_e32 v93, v206, v93
	v_mul_f32_e32 v94, v206, v94
	v_mul_f32_e32 v95, v206, v95
	v_mul_f32_e32 v96, v206, v96
	v_mul_f32_e32 v97, v206, v97
	s_mov_b32 vcc_hi, 0x437f0000
	v_med3_f32 v82, v82, 0, vcc_hi
	v_med3_f32 v83, v83, 0, vcc_hi
	v_med3_f32 v84, v84, 0, vcc_hi
	v_med3_f32 v85, v85, 0, vcc_hi
	v_med3_f32 v86, v86, 0, vcc_hi
	v_med3_f32 v87, v87, 0, vcc_hi
	v_med3_f32 v88, v88, 0, vcc_hi
	v_med3_f32 v89, v89, 0, vcc_hi
	v_med3_f32 v90, v90, 0, vcc_hi
	v_med3_f32 v91, v91, 0, vcc_hi
	v_med3_f32 v92, v92, 0, vcc_hi
	v_med3_f32 v93, v93, 0, vcc_hi
	v_med3_f32 v94, v94, 0, vcc_hi
	v_med3_f32 v95, v95, 0, vcc_hi
	v_med3_f32 v96, v96, 0, vcc_hi
	v_med3_f32 v97, v97, 0, vcc_hi
	v_cvt_i32_f32_e32 v82, v82
	v_cvt_i32_f32_e32 v83, v83
	v_cvt_i32_f32_e32 v84, v84
	v_cvt_i32_f32_e32 v85, v85
	v_cvt_i32_f32_e32 v86, v86
	v_cvt_i32_f32_e32 v87, v87
	v_cvt_i32_f32_e32 v88, v88
	v_cvt_i32_f32_e32 v89, v89
	v_cvt_i32_f32_e32 v90, v90
	v_cvt_i32_f32_e32 v91, v91
	v_cvt_i32_f32_e32 v92, v92
	v_cvt_i32_f32_e32 v93, v93
	v_cvt_i32_f32_e32 v94, v94
	v_cvt_i32_f32_e32 v95, v95
	v_cvt_i32_f32_e32 v96, v96
	v_cvt_i32_f32_e32 v97, v97
	v_mov_b32_e32 v252, 0
	v_add_u32_e32 v98, v201, v207
	v_cmp_lt_u32_e32 vcc, v208, v82
	s_nop 1
	v_cndmask_b32_e32 v229, v1, v210, vcc
	v_cmp_eq_u32_e32 vcc, v208, v82
	v_or_b32_e32 v252, v252, v229
	s_nop 0
	s_cbranch_vccz .Lcf_s0
	s_and_saveexec_b64 s[26:27], vcc
	ds_add_rtn_u32 v238, v209, v179
	s_waitcnt lgkmcnt(0)
	v_cmp_gt_u32_e64 s[0:1], s85, v238
	s_and_b64 exec, exec, s[0:1]
	v_not_b32_e32 v239, v50
	v_or_b32_e32 v253, 0x80000000, v50
	v_cmp_gt_i32_e64 s[0:1], 0, v50
	v_add_u32_e32 v129, 0, v98
	v_lshl_add_u32 v238, v238, 3, v226
	v_cndmask_b32_e64 v128, v253, v239, s[0:1]
	ds_write_b64 v238, v[128:129]
	s_mov_b64 exec, s[26:27]
